# ln2: the first selected expert's gather loads are issued before the token row's bf16->f32 conversion
# baseline (speedup 1.0000x reference)
.LBB0_1398:
	s_mov_b32 s7, 0
	s_branch .LBB0_1400
.LBB0_1400:
	v_cmp_lt_i32_e32 vcc, -1, v76
	s_nop 1
	s_and_b32 s12, vcc_lo, 0xffff
	s_cmp_eq_u32 s12, 0
	s_cbranch_scc1 .Lg_none
	s_ff1_i32_b32 s7, s12
	s_bitset0_b32 s12, s7
	v_readlane_b32 s2, v76, s7
	s_nop 1
	v_mov_b32_e32 v40, s2
	v_lshlrev_b64 v[94:95], 10, v[40:41]
	v_lshl_add_u64 v[94:95], v[36:37], 0, v[94:95]
	global_load_dword v96, v[94:95], off
	global_load_dword v97, v[94:95], off offset:256
	global_load_dword v98, v[94:95], off offset:512
	global_load_dword v99, v[94:95], off offset:768
	v_lshlrev_b32_e32 v64, 16, v56
	v_and_b32_e32 v65, 0xffff0000, v56
	v_lshlrev_b32_e32 v62, 16, v57
	v_and_b32_e32 v63, 0xffff0000, v57
	v_lshlrev_b32_e32 v60, 16, v54
	v_and_b32_e32 v61, 0xffff0000, v54
	v_lshlrev_b32_e32 v58, 16, v55
	v_and_b32_e32 v59, 0xffff0000, v55
	v_lshlrev_b32_e32 v56, 16, v52
	v_and_b32_e32 v57, 0xffff0000, v52
	v_lshlrev_b32_e32 v54, 16, v53
	v_and_b32_e32 v55, 0xffff0000, v53
	v_lshlrev_b32_e32 v78, 16, v50
	v_and_b32_e32 v79, 0xffff0000, v50
	v_lshlrev_b32_e32 v50, 16, v51
	v_and_b32_e32 v51, 0xffff0000, v51
	v_pk_mul_f32 v[52:53], v[50:51], s[4:5] op_sel_hi:[1,0]
	v_pk_mul_f32 v[50:51], v[78:79], s[4:5] op_sel_hi:[1,0]
	v_pk_mul_f32 v[54:55], v[54:55], s[4:5] op_sel_hi:[1,0]
	v_pk_mul_f32 v[56:57], v[56:57], s[4:5] op_sel_hi:[1,0]
	v_pk_mul_f32 v[58:59], v[58:59], s[4:5] op_sel_hi:[1,0]
	v_pk_mul_f32 v[60:61], v[60:61], s[4:5] op_sel_hi:[1,0]
	v_pk_mul_f32 v[62:63], v[62:63], s[4:5] op_sel_hi:[1,0]
	v_pk_mul_f32 v[64:65], v[64:65], s[4:5] op_sel_hi:[1,0]
	s_branch .Lg_after0

.Lg_after0:
	s_cmp_eq_u32 s12, 0
	s_cbranch_scc1 .Lg_cons1
	s_ff1_i32_b32 s7, s12
	s_bitset0_b32 s12, s7
	v_readlane_b32 s2, v76, s7
	s_nop 1
	v_mov_b32_e32 v40, s2
	v_lshlrev_b64 v[94:95], 10, v[40:41]
	v_lshl_add_u64 v[94:95], v[36:37], 0, v[94:95]
	global_load_dword v100, v[94:95], off
	global_load_dword v101, v[94:95], off offset:256
	global_load_dword v102, v[94:95], off offset:512
	global_load_dword v103, v[94:95], off offset:768
	s_cmp_eq_u32 s12, 0
	s_cbranch_scc1 .Lg_cons2
	s_ff1_i32_b32 s7, s12
	s_bitset0_b32 s12, s7
	v_readlane_b32 s2, v76, s7
	s_nop 1
	v_mov_b32_e32 v40, s2
	v_lshlrev_b64 v[94:95], 10, v[40:41]
	v_lshl_add_u64 v[94:95], v[36:37], 0, v[94:95]
	global_load_dword v104, v[94:95], off
	global_load_dword v105, v[94:95], off offset:256
	global_load_dword v106, v[94:95], off offset:512
	global_load_dword v107, v[94:95], off offset:768
	s_cmp_eq_u32 s12, 0
	s_cbranch_scc1 .Lg_cons3
	s_ff1_i32_b32 s7, s12
	s_bitset0_b32 s12, s7
	v_readlane_b32 s2, v76, s7
	s_nop 1
	v_mov_b32_e32 v40, s2
	v_lshlrev_b64 v[94:95], 10, v[40:41]
	v_lshl_add_u64 v[94:95], v[36:37], 0, v[94:95]
	global_load_dword v108, v[94:95], off
	global_load_dword v109, v[94:95], off offset:256
	global_load_dword v110, v[94:95], off offset:512
	global_load_dword v111, v[94:95], off offset:768

.Lg_none:
	v_lshlrev_b32_e32 v64, 16, v56
	v_and_b32_e32 v65, 0xffff0000, v56
	v_lshlrev_b32_e32 v62, 16, v57
	v_and_b32_e32 v63, 0xffff0000, v57
	v_lshlrev_b32_e32 v60, 16, v54
	v_and_b32_e32 v61, 0xffff0000, v54
	v_lshlrev_b32_e32 v58, 16, v55
	v_and_b32_e32 v59, 0xffff0000, v55
	v_lshlrev_b32_e32 v56, 16, v52
	v_and_b32_e32 v57, 0xffff0000, v52
	v_lshlrev_b32_e32 v54, 16, v53
	v_and_b32_e32 v55, 0xffff0000, v53
	v_lshlrev_b32_e32 v78, 16, v50
	v_and_b32_e32 v79, 0xffff0000, v50
	v_lshlrev_b32_e32 v50, 16, v51
	v_and_b32_e32 v51, 0xffff0000, v51
	v_pk_mul_f32 v[52:53], v[50:51], s[4:5] op_sel_hi:[1,0]
	v_pk_mul_f32 v[50:51], v[78:79], s[4:5] op_sel_hi:[1,0]
	v_pk_mul_f32 v[54:55], v[54:55], s[4:5] op_sel_hi:[1,0]
	v_pk_mul_f32 v[56:57], v[56:57], s[4:5] op_sel_hi:[1,0]
	v_pk_mul_f32 v[58:59], v[58:59], s[4:5] op_sel_hi:[1,0]
	v_pk_mul_f32 v[60:61], v[60:61], s[4:5] op_sel_hi:[1,0]
	v_pk_mul_f32 v[62:63], v[62:63], s[4:5] op_sel_hi:[1,0]
	v_pk_mul_f32 v[64:65], v[64:65], s[4:5] op_sel_hi:[1,0]
	s_branch .LBB0_1393
